# epiwide: O1 (EPI_PLAIN) GEMM epilogue widened to 16 dwordx4 stores per thread via v_permlane16_swap (was 32 dwordx2)
# speedup vs baseline: 1.0058x; 1.0042x over previous
; #define PG8_STAGE(bufoff, gbase, voff) do { _Pragma("unroll") for (int _i = 0; _i < 2; ++_i) \
;         __builtin_amdgcn_global_load_lds((const unsigned*)((const char*)(gbase) + (voff)[_i]), (PG8_LAS unsigned*)(lds + (bufoff) + ldsw + _i * 8192), 16, 0, 0); } while (0)
; #define PG8_LDA(dst, b, h) do { _Pragma("unroll") for (int m = 0; m < 4; ++m) _Pragma("unroll") for (int k = 0; k < 2; ++k) dst[m][k] = *(const PG8_LAS bf16x8*)(lds + PG8_SA(b, h) + aoff + m * 2048 + k * 1024); } while (0)
; #define PG8_WAIT_V(n) asm volatile("s_waitcnt vmcnt(" #n ")" ::: "memory")
; #define PG8_WAIT_L(n) asm volatile("s_waitcnt lgkmcnt(" #n ")" ::: "memory")
; template <class Epi>
; __device__ __forceinline__ void gemm_phase(PG8_LAS unsigned char* lds, const Gemm g, const Sched& S, const Epi& E) {
;     ...
;         for (int t = 0; t < nt; t += 2) {
;             const bool last = (t == nt - 2);
;             const char* a1 = cA + (size_t)(t + 1) * kstep;
;             const char* a2 = last ? nA : cA + (size_t)(t + 2) * kstep; const char* b2 = last ? nB : cB + (size_t)(t + 2) * kstep;
;             const char* a3 = a2 + kstep; const char* b3 = b2 + kstep;
;             PG8_LDB(B0, 0, 0); PG8_SCHED; PG8_LDA(At, 0, 0); PG8_STAGE(PG8_SA(1, 1), a1 + hsA, voffA);
;             PG8_WAIT_L(8); PG8_BAR; PG8_WAIT_L(0); PG8_MMA(0, 0, At, B0); PG8_BAR; PG8_SCHED;
;             PG8_LDB(B1, 0, 1); PG8_STAGE(PG8_SB(0, 0), b2, voffB);
;             PG8_BAR; PG8_WAIT_L(0); PG8_MMA(0, 1, At, B1); PG8_BAR;
;             PG8_LDA(At, 0, 1); PG8_STAGE(PG8_SA(0, 0), a2, voffA);
;             PG8_BAR; PG8_WAIT_L(0); PG8_MMA(1, 0, At, B0); PG8_BAR; PG8_SCHED;
;             PG8_STAGE(PG8_SB(0, 1), b2 + hsB, voffB);
;             PG8_WAIT_V(6); PG8_BAR; PG8_MMA(1, 1, At, B1); PG8_BAR;
;             PG8_LDB(B0, 1, 0); PG8_SCHED; PG8_LDA(At, 1, 0); PG8_STAGE(PG8_SA(0, 1), a2 + hsA, voffA);
;             PG8_WAIT_L(8); PG8_BAR; PG8_WAIT_L(0); PG8_MMA(0, 0, At, B0); PG8_BAR; PG8_SCHED;
;             PG8_LDB(B1, 1, 1); PG8_STAGE(PG8_SB(1, 0), b3, voffB);
;             PG8_BAR; PG8_WAIT_L(0); PG8_MMA(0, 1, At, B1); PG8_BAR;
;             PG8_LDA(At, 1, 1); PG8_STAGE(PG8_SA(1, 0), a3, voffA);
;             PG8_BAR; PG8_WAIT_L(0); PG8_MMA(1, 0, At, B0); PG8_BAR; PG8_SCHED;
;             PG8_STAGE(PG8_SB(1, 1), b3 + hsB, voffB);
;             PG8_WAIT_V(6); PG8_BAR; PG8_MMA(1, 1, At, B1); PG8_BAR;
.LBB0_317:
	s_add_u32 s14, s12, 0xfffc0080
	s_addc_u32 s15, s13, -1
	s_add_i32 s50, 0, 0x10000
	v_add_u32_e32 v145, s50, v135
	ds_read_b128 v[146:149], v145
	ds_read_b128 v[150:153], v145 offset:1024
	ds_read_b128 v[154:157], v145 offset:2048
	ds_read_b128 v[158:161], v145 offset:3072
	s_cmp_eq_u32 s49, 12
	s_cselect_b32 s17, s2, s15
	s_cselect_b32 s16, s3, s14
	s_cselect_b32 s15, s5, s39
	s_cselect_b32 s14, s37, s38
	v_lshl_add_u64 v[162:163], s[12:13], 0, v[130:131]
	s_add_i32 m0, s7, 0xc000
	ds_read_b128 v[172:175], v144
	ds_read_b128 v[178:181], v144 offset:1024
	ds_read_b128 v[182:185], v144 offset:2048
	ds_read_b128 v[186:189], v144 offset:3072
	ds_read_b128 v[190:193], v144 offset:4096
	ds_read_b128 v[194:197], v144 offset:5120
	ds_read_b128 v[198:201], v144 offset:6144
	ds_read_b128 v[202:205], v144 offset:7168
	global_load_lds_dwordx4 v[162:163], off
	v_lshl_add_u64 v[162:163], s[12:13], 0, v[132:133]
	s_add_i32 m0, s7, 0xe000
	s_nop 0
	global_load_lds_dwordx4 v[162:163], off
	s_waitcnt lgkmcnt(8)
	s_barrier
	s_waitcnt lgkmcnt(0)
	s_setprio 1
	s_waitcnt lgkmcnt(0)
	v_mfma_f32_16x16x32_bf16 v[124:127], v[146:149], v[172:175], v[124:127]
	v_mfma_f32_16x16x32_bf16 v[120:123], v[154:157], v[172:175], v[120:123]
	v_mfma_f32_16x16x32_bf16 v[116:119], v[146:149], v[182:185], v[116:119]
	v_mfma_f32_16x16x32_bf16 v[104:107], v[154:157], v[182:185], v[104:107]
	v_mfma_f32_16x16x32_bf16 v[100:103], v[146:149], v[190:193], v[100:103]
	v_mfma_f32_16x16x32_bf16 v[88:91], v[154:157], v[190:193], v[88:91]
	v_mfma_f32_16x16x32_bf16 v[84:87], v[146:149], v[198:201], v[84:87]
	v_mfma_f32_16x16x32_bf16 v[72:75], v[154:157], v[198:201], v[72:75]
	v_mfma_f32_16x16x32_bf16 v[124:127], v[150:153], v[178:181], v[124:127]
	v_mfma_f32_16x16x32_bf16 v[120:123], v[158:161], v[178:181], v[120:123]
	v_mfma_f32_16x16x32_bf16 v[116:119], v[150:153], v[186:189], v[116:119]
	v_mfma_f32_16x16x32_bf16 v[104:107], v[158:161], v[186:189], v[104:107]
	v_mfma_f32_16x16x32_bf16 v[100:103], v[150:153], v[194:197], v[100:103]
	v_mfma_f32_16x16x32_bf16 v[88:91], v[158:161], v[194:197], v[88:91]
	v_mfma_f32_16x16x32_bf16 v[84:87], v[150:153], v[202:205], v[84:87]
	v_mfma_f32_16x16x32_bf16 v[72:75], v[158:161], v[202:205], v[72:75]
	s_setprio 0
	s_barrier
	s_add_i32 s52, 0, 0x14000
	s_add_i32 s50, s50, s23
	v_add_u32_e32 v145, s52, v135
	v_lshl_add_u64 v[162:163], s[14:15], 0, v[166:167]
	s_mov_b32 m0, s50
	ds_read_b128 v[206:209], v145
	ds_read_b128 v[210:213], v145 offset:1024
	ds_read_b128 v[236:239], v145 offset:2048
	ds_read_b128 v[240:243], v145 offset:3072
	global_load_lds_dwordx4 v[162:163], off
	v_lshl_add_u64 v[214:215], s[14:15], 0, v[128:129]
	s_add_i32 m0, s50, 0x2000
	s_nop 0
	global_load_lds_dwordx4 v[214:215], off
	s_barrier
	s_waitcnt lgkmcnt(0)
	s_setprio 1
	s_waitcnt lgkmcnt(0)
	v_mfma_f32_16x16x32_bf16 v[112:115], v[206:209], v[172:175], v[112:115]
	v_mfma_f32_16x16x32_bf16 v[108:111], v[236:239], v[172:175], v[108:111]
	v_mfma_f32_16x16x32_bf16 v[96:99], v[206:209], v[182:185], v[96:99]
	v_mfma_f32_16x16x32_bf16 v[92:95], v[236:239], v[182:185], v[92:95]
	v_mfma_f32_16x16x32_bf16 v[80:83], v[206:209], v[190:193], v[80:83]
	v_mfma_f32_16x16x32_bf16 v[76:79], v[236:239], v[190:193], v[76:79]
	v_mfma_f32_16x16x32_bf16 v[68:71], v[206:209], v[198:201], v[68:71]
	v_mfma_f32_16x16x32_bf16 v[64:67], v[236:239], v[198:201], v[64:67]
	v_mfma_f32_16x16x32_bf16 v[112:115], v[210:213], v[178:181], v[112:115]
	v_mfma_f32_16x16x32_bf16 v[108:111], v[240:243], v[178:181], v[108:111]
	v_mfma_f32_16x16x32_bf16 v[96:99], v[210:213], v[186:189], v[96:99]
	v_mfma_f32_16x16x32_bf16 v[92:95], v[240:243], v[186:189], v[92:95]
	v_mfma_f32_16x16x32_bf16 v[80:83], v[210:213], v[194:197], v[80:83]
	v_mfma_f32_16x16x32_bf16 v[76:79], v[240:243], v[194:197], v[76:79]
	v_mfma_f32_16x16x32_bf16 v[68:71], v[210:213], v[202:205], v[68:71]
	v_mfma_f32_16x16x32_bf16 v[64:67], v[240:243], v[202:205], v[64:67]
	s_setprio 0
	s_mov_b32 m0, s7
	v_lshl_add_u64 v[244:245], s[16:17], 0, v[166:167]
	s_barrier
	ds_read_b128 v[172:175], v144 offset:16384
	ds_read_b128 v[178:181], v144 offset:17408
	ds_read_b128 v[182:185], v144 offset:18432
	ds_read_b128 v[186:189], v144 offset:19456
	ds_read_b128 v[190:193], v144 offset:20480
	ds_read_b128 v[194:197], v144 offset:21504
	ds_read_b128 v[198:201], v144 offset:22528
	ds_read_b128 v[202:205], v144 offset:23552
	global_load_lds_dwordx4 v[244:245], off
	v_lshl_add_u64 v[246:247], s[16:17], 0, v[128:129]
	s_mov_b32 m0, s24
	s_nop 0
	global_load_lds_dwordx4 v[246:247], off
	s_barrier
	s_waitcnt lgkmcnt(0)
	s_setprio 1
	s_waitcnt lgkmcnt(0)
	v_mfma_f32_16x16x32_bf16 v[60:63], v[146:149], v[172:175], v[60:63]
	v_mfma_f32_16x16x32_bf16 v[56:59], v[154:157], v[172:175], v[56:59]
	v_mfma_f32_16x16x32_bf16 v[52:55], v[146:149], v[182:185], v[52:55]
	v_mfma_f32_16x16x32_bf16 v[40:43], v[154:157], v[182:185], v[40:43]
	v_mfma_f32_16x16x32_bf16 v[36:39], v[146:149], v[190:193], v[36:39]
	v_mfma_f32_16x16x32_bf16 v[24:27], v[154:157], v[190:193], v[24:27]
	v_mfma_f32_16x16x32_bf16 v[20:23], v[146:149], v[198:201], v[20:23]
	v_mfma_f32_16x16x32_bf16 v[8:11], v[154:157], v[198:201], v[8:11]
	v_mfma_f32_16x16x32_bf16 v[60:63], v[150:153], v[178:181], v[60:63]
	v_mfma_f32_16x16x32_bf16 v[56:59], v[158:161], v[178:181], v[56:59]
	v_mfma_f32_16x16x32_bf16 v[52:55], v[150:153], v[186:189], v[52:55]
	v_mfma_f32_16x16x32_bf16 v[40:43], v[158:161], v[186:189], v[40:43]
	v_mfma_f32_16x16x32_bf16 v[36:39], v[150:153], v[194:197], v[36:39]
	v_mfma_f32_16x16x32_bf16 v[24:27], v[158:161], v[194:197], v[24:27]
	v_mfma_f32_16x16x32_bf16 v[20:23], v[150:153], v[202:205], v[20:23]
	v_mfma_f32_16x16x32_bf16 v[8:11], v[158:161], v[202:205], v[8:11]
	s_setprio 0
	s_barrier
; #define PG8_STAGE(bufoff, gbase, voff) do { _Pragma("unroll") for (int _i = 0; _i < 2; ++_i) \
;         __builtin_amdgcn_global_load_lds((const unsigned*)((const char*)(gbase) + (voff)[_i]), (PG8_LAS unsigned*)(lds + (bufoff) + ldsw + _i * 8192), 16, 0, 0); } while (0)
; #define PG8_LDA(dst, b, h) do { _Pragma("unroll") for (int m = 0; m < 4; ++m) _Pragma("unroll") for (int k = 0; k < 2; ++k) dst[m][k] = *(const PG8_LAS bf16x8*)(lds + PG8_SA(b, h) + aoff + m * 2048 + k * 1024); } while (0)
; #define PG8_WAIT_V(n) asm volatile("s_waitcnt vmcnt(" #n ")" ::: "memory")
; #define PG8_WAIT_L(n) asm volatile("s_waitcnt lgkmcnt(" #n ")" ::: "memory")
; template <class Epi>
; __device__ __forceinline__ void gemm_phase(PG8_LAS unsigned char* lds, const Gemm g, const Sched& S, const Epi& E) {
;     ...
;         for (int t = 0; t < nt; t += 2) {
;             const bool last = (t == nt - 2);
;             const char* a1 = cA + (size_t)(t + 1) * kstep;
;             const char* a2 = last ? nA : cA + (size_t)(t + 2) * kstep; const char* b2 = last ? nB : cB + (size_t)(t + 2) * kstep;
;             const char* a3 = a2 + kstep; const char* b3 = b2 + kstep;
;             PG8_LDB(B0, 0, 0); PG8_SCHED; PG8_LDA(At, 0, 0); PG8_STAGE(PG8_SA(1, 1), a1 + hsA, voffA);
;             PG8_WAIT_L(8); PG8_BAR; PG8_WAIT_L(0); PG8_MMA(0, 0, At, B0); PG8_BAR; PG8_SCHED;
;             PG8_LDB(B1, 0, 1); PG8_STAGE(PG8_SB(0, 0), b2, voffB);
;             PG8_BAR; PG8_WAIT_L(0); PG8_MMA(0, 1, At, B1); PG8_BAR;
;             PG8_LDA(At, 0, 1); PG8_STAGE(PG8_SA(0, 0), a2, voffA);
;             PG8_BAR; PG8_WAIT_L(0); PG8_MMA(1, 0, At, B0); PG8_BAR; PG8_SCHED;
;             PG8_STAGE(PG8_SB(0, 1), b2 + hsB, voffB);
;             PG8_WAIT_V(6); PG8_BAR; PG8_MMA(1, 1, At, B1); PG8_BAR;
;             PG8_LDB(B0, 1, 0); PG8_SCHED; PG8_LDA(At, 1, 0); PG8_STAGE(PG8_SA(0, 1), a2 + hsA, voffA);
;             PG8_WAIT_L(8); PG8_BAR; PG8_WAIT_L(0); PG8_MMA(0, 0, At, B0); PG8_BAR; PG8_SCHED;
;             PG8_LDB(B1, 1, 1); PG8_STAGE(PG8_SB(1, 0), b3, voffB);
;             PG8_BAR; PG8_WAIT_L(0); PG8_MMA(0, 1, At, B1); PG8_BAR;
;             PG8_LDA(At, 1, 1); PG8_STAGE(PG8_SA(1, 0), a3, voffA);
;             PG8_BAR; PG8_WAIT_L(0); PG8_MMA(1, 0, At, B0); PG8_BAR; PG8_SCHED;
;             PG8_STAGE(PG8_SB(1, 1), b3 + hsB, voffB);
;             PG8_WAIT_V(6); PG8_BAR; PG8_MMA(1, 1, At, B1); PG8_BAR;
	s_add_u32 s50, s14, 0x40000
	s_addc_u32 s51, s15, 0
	s_add_i32 s52, s52, s23
	v_lshl_add_u64 v[146:147], s[50:51], 0, v[166:167]
	s_mov_b32 m0, s52
	s_nop 0
	global_load_lds_dwordx4 v[146:147], off
	v_lshl_add_u64 v[146:147], s[50:51], 0, v[128:129]
	s_add_i32 m0, s52, 0x2000
	s_nop 0
	global_load_lds_dwordx4 v[146:147], off
	s_waitcnt vmcnt(6)
	s_barrier
	s_setprio 1
	v_mfma_f32_16x16x32_bf16 v[48:51], v[206:209], v[172:175], v[48:51]
	v_mfma_f32_16x16x32_bf16 v[44:47], v[236:239], v[172:175], v[44:47]
	v_mfma_f32_16x16x32_bf16 v[32:35], v[206:209], v[182:185], v[32:35]
	v_mfma_f32_16x16x32_bf16 v[28:31], v[236:239], v[182:185], v[28:31]
	v_mfma_f32_16x16x32_bf16 v[16:19], v[206:209], v[190:193], v[16:19]
	v_mfma_f32_16x16x32_bf16 v[12:15], v[236:239], v[190:193], v[12:15]
	v_mfma_f32_16x16x32_bf16 v[4:7], v[206:209], v[198:201], v[4:7]
	v_mfma_f32_16x16x32_bf16 v[0:3], v[236:239], v[198:201], v[0:3]
	v_mfma_f32_16x16x32_bf16 v[48:51], v[210:213], v[178:181], v[48:51]
	v_mfma_f32_16x16x32_bf16 v[44:47], v[240:243], v[178:181], v[44:47]
	v_mfma_f32_16x16x32_bf16 v[32:35], v[210:213], v[186:189], v[32:35]
	v_mfma_f32_16x16x32_bf16 v[28:31], v[240:243], v[186:189], v[28:31]
	v_mfma_f32_16x16x32_bf16 v[16:19], v[210:213], v[194:197], v[16:19]
	v_mfma_f32_16x16x32_bf16 v[12:15], v[240:243], v[194:197], v[12:15]
	v_mfma_f32_16x16x32_bf16 v[4:7], v[210:213], v[202:205], v[4:7]
	v_mfma_f32_16x16x32_bf16 v[0:3], v[240:243], v[202:205], v[0:3]
	s_setprio 0
	s_add_i32 s50, 0, 0x18000
	v_add_u32_e32 v145, s50, v135
	s_barrier
	ds_read_b128 v[146:149], v145
	ds_read_b128 v[150:153], v145 offset:1024
	ds_read_b128 v[154:157], v145 offset:2048
	ds_read_b128 v[158:161], v145 offset:3072
	s_add_u32 s16, s16, 0x40000
	s_addc_u32 s17, s17, 0
	s_mov_b32 m0, s25
	v_lshl_add_u64 v[206:207], s[16:17], 0, v[166:167]
	ds_read_b128 v[172:175], v144 offset:32768
	ds_read_b128 v[178:181], v144 offset:33792
	ds_read_b128 v[182:185], v144 offset:34816
	ds_read_b128 v[186:189], v144 offset:35840
	ds_read_b128 v[190:193], v144 offset:36864
	ds_read_b128 v[194:197], v144 offset:37888
	ds_read_b128 v[198:201], v144 offset:38912
	ds_read_b128 v[202:205], v144 offset:39936
	global_load_lds_dwordx4 v[206:207], off
	v_lshl_add_u64 v[206:207], s[16:17], 0, v[128:129]
	s_mov_b32 m0, s26
	s_nop 0
	global_load_lds_dwordx4 v[206:207], off
	s_waitcnt lgkmcnt(8)
	s_barrier
	s_waitcnt lgkmcnt(0)
	s_setprio 1
	s_waitcnt lgkmcnt(0)
	v_mfma_f32_16x16x32_bf16 v[124:127], v[146:149], v[172:175], v[124:127]
	v_mfma_f32_16x16x32_bf16 v[120:123], v[154:157], v[172:175], v[120:123]
	v_mfma_f32_16x16x32_bf16 v[116:119], v[146:149], v[182:185], v[116:119]
	v_mfma_f32_16x16x32_bf16 v[104:107], v[154:157], v[182:185], v[104:107]
	v_mfma_f32_16x16x32_bf16 v[100:103], v[146:149], v[190:193], v[100:103]
	v_mfma_f32_16x16x32_bf16 v[88:91], v[154:157], v[190:193], v[88:91]
	v_mfma_f32_16x16x32_bf16 v[84:87], v[146:149], v[198:201], v[84:87]
	v_mfma_f32_16x16x32_bf16 v[72:75], v[154:157], v[198:201], v[72:75]
	v_mfma_f32_16x16x32_bf16 v[124:127], v[150:153], v[178:181], v[124:127]
	v_mfma_f32_16x16x32_bf16 v[120:123], v[158:161], v[178:181], v[120:123]
	v_mfma_f32_16x16x32_bf16 v[116:119], v[150:153], v[186:189], v[116:119]
	v_mfma_f32_16x16x32_bf16 v[104:107], v[158:161], v[186:189], v[104:107]
	v_mfma_f32_16x16x32_bf16 v[100:103], v[150:153], v[194:197], v[100:103]
	v_mfma_f32_16x16x32_bf16 v[88:91], v[158:161], v[194:197], v[88:91]
	v_mfma_f32_16x16x32_bf16 v[84:87], v[150:153], v[202:205], v[84:87]
	v_mfma_f32_16x16x32_bf16 v[72:75], v[158:161], v[202:205], v[72:75]
	s_setprio 0
	s_barrier
	s_add_i32 s16, 0, 0x1c000
	s_add_i32 s17, s50, s23
	v_add_u32_e32 v145, s16, v135
	v_lshl_add_u64 v[162:163], v[162:163], 0, s[76:77]
	s_mov_b32 m0, s17
	ds_read_b128 v[206:209], v145
	ds_read_b128 v[210:213], v145 offset:1024
	ds_read_b128 v[236:239], v145 offset:2048
	ds_read_b128 v[240:243], v145 offset:3072
	global_load_lds_dwordx4 v[162:163], off
	v_lshl_add_u64 v[162:163], v[214:215], 0, s[76:77]
	s_add_i32 m0, s17, 0x2000
	s_nop 0
	global_load_lds_dwordx4 v[162:163], off
	s_barrier
	s_waitcnt lgkmcnt(0)
	s_setprio 1
	s_waitcnt lgkmcnt(0)
	v_mfma_f32_16x16x32_bf16 v[112:115], v[206:209], v[172:175], v[112:115]
	v_mfma_f32_16x16x32_bf16 v[108:111], v[236:239], v[172:175], v[108:111]
	v_mfma_f32_16x16x32_bf16 v[96:99], v[206:209], v[182:185], v[96:99]
	v_mfma_f32_16x16x32_bf16 v[92:95], v[236:239], v[182:185], v[92:95]
	v_mfma_f32_16x16x32_bf16 v[80:83], v[206:209], v[190:193], v[80:83]
	v_mfma_f32_16x16x32_bf16 v[76:79], v[236:239], v[190:193], v[76:79]
	v_mfma_f32_16x16x32_bf16 v[68:71], v[206:209], v[198:201], v[68:71]
	v_mfma_f32_16x16x32_bf16 v[64:67], v[236:239], v[198:201], v[64:67]
	v_mfma_f32_16x16x32_bf16 v[112:115], v[210:213], v[178:181], v[112:115]
	v_mfma_f32_16x16x32_bf16 v[108:111], v[240:243], v[178:181], v[108:111]
	v_mfma_f32_16x16x32_bf16 v[96:99], v[210:213], v[186:189], v[96:99]
	v_mfma_f32_16x16x32_bf16 v[92:95], v[240:243], v[186:189], v[92:95]
	v_mfma_f32_16x16x32_bf16 v[80:83], v[210:213], v[194:197], v[80:83]
	v_mfma_f32_16x16x32_bf16 v[76:79], v[240:243], v[194:197], v[76:79]
	v_mfma_f32_16x16x32_bf16 v[68:71], v[210:213], v[202:205], v[68:71]
	v_mfma_f32_16x16x32_bf16 v[64:67], v[240:243], v[202:205], v[64:67]
	s_setprio 0
	s_mov_b32 m0, s27
	v_lshl_add_u64 v[162:163], v[244:245], 0, s[76:77]
	s_barrier
	ds_read_b128 v[172:175], v144 offset:49152
	ds_read_b128 v[178:181], v144 offset:50176
	ds_read_b128 v[182:185], v144 offset:51200
	ds_read_b128 v[186:189], v144 offset:52224
	ds_read_b128 v[190:193], v144 offset:53248
	ds_read_b128 v[194:197], v144 offset:54272
	ds_read_b128 v[198:201], v144 offset:55296
	ds_read_b128 v[202:205], v144 offset:56320
	global_load_lds_dwordx4 v[162:163], off
	v_lshl_add_u64 v[162:163], v[246:247], 0, s[76:77]
	s_mov_b32 m0, s29
	s_nop 0
	global_load_lds_dwordx4 v[162:163], off
	s_barrier
; #define PG8_STAGE(bufoff, gbase, voff) do { _Pragma("unroll") for (int _i = 0; _i < 2; ++_i) \
;         __builtin_amdgcn_global_load_lds((const unsigned*)((const char*)(gbase) + (voff)[_i]), (PG8_LAS unsigned*)(lds + (bufoff) + ldsw + _i * 8192), 16, 0, 0); } while (0)
; #define PG8_LDA(dst, b, h) do { _Pragma("unroll") for (int m = 0; m < 4; ++m) _Pragma("unroll") for (int k = 0; k < 2; ++k) dst[m][k] = *(const PG8_LAS bf16x8*)(lds + PG8_SA(b, h) + aoff + m * 2048 + k * 1024); } while (0)
; #define PG8_WAIT_V(n) asm volatile("s_waitcnt vmcnt(" #n ")" ::: "memory")
; #define PG8_WAIT_L(n) asm volatile("s_waitcnt lgkmcnt(" #n ")" ::: "memory")
; template <class Epi>
; __device__ __forceinline__ void gemm_phase(PG8_LAS unsigned char* lds, const Gemm g, const Sched& S, const Epi& E) {
;     ...
;         for (int t = 0; t < nt; t += 2) {
;             const bool last = (t == nt - 2);
;             const char* a1 = cA + (size_t)(t + 1) * kstep;
;             const char* a2 = last ? nA : cA + (size_t)(t + 2) * kstep; const char* b2 = last ? nB : cB + (size_t)(t + 2) * kstep;
;             const char* a3 = a2 + kstep; const char* b3 = b2 + kstep;
;             PG8_LDB(B0, 0, 0); PG8_SCHED; PG8_LDA(At, 0, 0); PG8_STAGE(PG8_SA(1, 1), a1 + hsA, voffA);
;             PG8_WAIT_L(8); PG8_BAR; PG8_WAIT_L(0); PG8_MMA(0, 0, At, B0); PG8_BAR; PG8_SCHED;
;             PG8_LDB(B1, 0, 1); PG8_STAGE(PG8_SB(0, 0), b2, voffB);
;             PG8_BAR; PG8_WAIT_L(0); PG8_MMA(0, 1, At, B1); PG8_BAR;
;             PG8_LDA(At, 0, 1); PG8_STAGE(PG8_SA(0, 0), a2, voffA);
;             PG8_BAR; PG8_WAIT_L(0); PG8_MMA(1, 0, At, B0); PG8_BAR; PG8_SCHED;
;             PG8_STAGE(PG8_SB(0, 1), b2 + hsB, voffB);
;             PG8_WAIT_V(6); PG8_BAR; PG8_MMA(1, 1, At, B1); PG8_BAR;
;             PG8_LDB(B0, 1, 0); PG8_SCHED; PG8_LDA(At, 1, 0); PG8_STAGE(PG8_SA(0, 1), a2 + hsA, voffA);
;             PG8_WAIT_L(8); PG8_BAR; PG8_WAIT_L(0); PG8_MMA(0, 0, At, B0); PG8_BAR; PG8_SCHED;
;             PG8_LDB(B1, 1, 1); PG8_STAGE(PG8_SB(1, 0), b3, voffB);
;             PG8_BAR; PG8_WAIT_L(0); PG8_MMA(0, 1, At, B1); PG8_BAR;
;             PG8_LDA(At, 1, 1); PG8_STAGE(PG8_SA(1, 0), a3, voffA);
;             PG8_BAR; PG8_WAIT_L(0); PG8_MMA(1, 0, At, B0); PG8_BAR; PG8_SCHED;
;             PG8_STAGE(PG8_SB(1, 1), b3 + hsB, voffB);
;             PG8_WAIT_V(6); PG8_BAR; PG8_MMA(1, 1, At, B1); PG8_BAR;
	s_waitcnt lgkmcnt(0)
	s_setprio 1
	s_waitcnt lgkmcnt(0)
	v_mfma_f32_16x16x32_bf16 v[60:63], v[146:149], v[172:175], v[60:63]
	v_mfma_f32_16x16x32_bf16 v[56:59], v[154:157], v[172:175], v[56:59]
	v_mfma_f32_16x16x32_bf16 v[52:55], v[146:149], v[182:185], v[52:55]
	v_mfma_f32_16x16x32_bf16 v[40:43], v[154:157], v[182:185], v[40:43]
	v_mfma_f32_16x16x32_bf16 v[36:39], v[146:149], v[190:193], v[36:39]
	v_mfma_f32_16x16x32_bf16 v[24:27], v[154:157], v[190:193], v[24:27]
	v_mfma_f32_16x16x32_bf16 v[20:23], v[146:149], v[198:201], v[20:23]
	v_mfma_f32_16x16x32_bf16 v[8:11], v[154:157], v[198:201], v[8:11]
	v_mfma_f32_16x16x32_bf16 v[60:63], v[150:153], v[178:181], v[60:63]
	v_mfma_f32_16x16x32_bf16 v[56:59], v[158:161], v[178:181], v[56:59]
	v_mfma_f32_16x16x32_bf16 v[52:55], v[150:153], v[186:189], v[52:55]
	v_mfma_f32_16x16x32_bf16 v[40:43], v[158:161], v[186:189], v[40:43]
	v_mfma_f32_16x16x32_bf16 v[36:39], v[150:153], v[194:197], v[36:39]
	v_mfma_f32_16x16x32_bf16 v[24:27], v[158:161], v[194:197], v[24:27]
	v_mfma_f32_16x16x32_bf16 v[20:23], v[150:153], v[202:205], v[20:23]
	v_mfma_f32_16x16x32_bf16 v[8:11], v[158:161], v[202:205], v[8:11]
	s_setprio 0
	s_barrier
	s_add_u32 s14, s14, 0x40080
	s_addc_u32 s15, s15, 0
	s_add_i32 s16, s16, s23
	v_lshl_add_u64 v[146:147], s[14:15], 0, v[166:167]
	s_mov_b32 m0, s16
	s_nop 0
	global_load_lds_dwordx4 v[146:147], off
	v_lshl_add_u64 v[146:147], s[14:15], 0, v[128:129]
	s_add_i32 m0, s16, 0x2000
	s_nop 0
	global_load_lds_dwordx4 v[146:147], off
	s_waitcnt vmcnt(6)
	s_barrier
	s_setprio 1
	v_mfma_f32_16x16x32_bf16 v[48:51], v[206:209], v[172:175], v[48:51]
	v_mfma_f32_16x16x32_bf16 v[44:47], v[236:239], v[172:175], v[44:47]
	v_mfma_f32_16x16x32_bf16 v[32:35], v[206:209], v[182:185], v[32:35]
	v_mfma_f32_16x16x32_bf16 v[28:31], v[236:239], v[182:185], v[28:31]
	v_mfma_f32_16x16x32_bf16 v[16:19], v[206:209], v[190:193], v[16:19]
	v_mfma_f32_16x16x32_bf16 v[12:15], v[236:239], v[190:193], v[12:15]
	v_mfma_f32_16x16x32_bf16 v[4:7], v[206:209], v[198:201], v[4:7]
	v_mfma_f32_16x16x32_bf16 v[0:3], v[236:239], v[198:201], v[0:3]
	v_mfma_f32_16x16x32_bf16 v[48:51], v[210:213], v[178:181], v[48:51]
	v_mfma_f32_16x16x32_bf16 v[44:47], v[240:243], v[178:181], v[44:47]
	v_mfma_f32_16x16x32_bf16 v[32:35], v[210:213], v[186:189], v[32:35]
	v_mfma_f32_16x16x32_bf16 v[28:31], v[240:243], v[186:189], v[28:31]
	v_mfma_f32_16x16x32_bf16 v[16:19], v[210:213], v[194:197], v[16:19]
	v_mfma_f32_16x16x32_bf16 v[12:15], v[240:243], v[194:197], v[12:15]
	v_mfma_f32_16x16x32_bf16 v[4:7], v[210:213], v[202:205], v[4:7]
	v_mfma_f32_16x16x32_bf16 v[0:3], v[240:243], v[202:205], v[0:3]
	s_setprio 0
	s_add_i32 s49, s49, 2
	s_add_u32 s12, s12, 0x100
	s_addc_u32 s13, s13, 0
	s_add_u32 s38, s38, 0x100
	s_addc_u32 s39, s39, 0
	s_cmp_gt_u32 s49, 13
	s_barrier
	s_cbranch_scc0 .LBB0_317
; __device__ __forceinline__ uint32_t pack2(float a, float b) { uint32_t r; asm("v_cvt_pk_bf16_f32 %0, %1, %2" : "=v"(r) : "v"(a), "v"(b)); return r; }
;   __device__ __forceinline__ void operator()(const f32x4 (&acc)[2][2][4][2], const pg8::Unit& u, int wr, int wc, int fr, int fq) const {
;     ...
;         } else {
;           float rsv = (kind == EPI_ROWSCALE) ? rs[(size_t)row * 2] : 1.0f;
; #pragma unroll
;           for (int bj = 0; bj < 2; ++bj)
; #pragma unroll
;             for (int n = 0; n < 2; ++n) {
;               int cc = u.pn * 256 + bj * 128 + wc * 32 + n * 16 + fq * 4;
;               f32x4 a = acc[ai][bj][m][n];
;               uint2 o; o.x = pack2(a[0] * rsv, a[1] * rsv); o.y = pack2(a[2] * rsv, a[3] * rsv);
;               *(uint2*)(outb + (size_t)row * ldo + cc) = o;
;             }
	s_lshl_b32 s2, s6, 8
	v_and_b32_e32 v146, 16, v231
	v_lshrrev_b32_e32 v147, 1, v146
	v_add_u32_e32 v146, v146, v147
	v_lshl_or_b32 v148, s36, 8, v143
	v_lshl_add_u32 v194, v148, 1, v146
	v_mov_b32_e32 v195, 0
	v_add_u32_e32 v178, s2, v134
	v_ashrrev_i32_e32 v179, 31, v178
	v_lshlrev_b64 v[178:179], 12, v[178:179]
	v_lshl_add_u64 v[178:179], s[42:43], 0, v[178:179]
	v_lshl_add_u64 v[178:179], v[178:179], 0, v[194:195]
	v_add_u32_e32 v180, s2, v136
	v_ashrrev_i32_e32 v181, 31, v180
	v_lshlrev_b64 v[180:181], 12, v[180:181]
	v_lshl_add_u64 v[180:181], s[42:43], 0, v[180:181]
	v_lshl_add_u64 v[180:181], v[180:181], 0, v[194:195]
	v_add_u32_e32 v182, s2, v137
	v_ashrrev_i32_e32 v183, 31, v182
	v_lshlrev_b64 v[182:183], 12, v[182:183]
	v_lshl_add_u64 v[182:183], s[42:43], 0, v[182:183]
	v_lshl_add_u64 v[182:183], v[182:183], 0, v[194:195]
	v_add_u32_e32 v184, s2, v138
	v_ashrrev_i32_e32 v185, 31, v184
	v_lshlrev_b64 v[184:185], 12, v[184:185]
	v_lshl_add_u64 v[184:185], s[42:43], 0, v[184:185]
	v_lshl_add_u64 v[184:185], v[184:185], 0, v[194:195]
	v_add_u32_e32 v186, s2, v139
	v_ashrrev_i32_e32 v187, 31, v186
	v_lshlrev_b64 v[186:187], 12, v[186:187]
	v_lshl_add_u64 v[186:187], s[42:43], 0, v[186:187]
	v_lshl_add_u64 v[186:187], v[186:187], 0, v[194:195]
	v_add_u32_e32 v188, s2, v140
	v_ashrrev_i32_e32 v189, 31, v188
	v_lshlrev_b64 v[188:189], 12, v[188:189]
	v_lshl_add_u64 v[188:189], s[42:43], 0, v[188:189]
	v_lshl_add_u64 v[188:189], v[188:189], 0, v[194:195]
	v_add_u32_e32 v190, s2, v141
	v_ashrrev_i32_e32 v191, 31, v190
	v_lshlrev_b64 v[190:191], 12, v[190:191]
	v_lshl_add_u64 v[190:191], s[42:43], 0, v[190:191]
	v_lshl_add_u64 v[190:191], v[190:191], 0, v[194:195]
	v_add_u32_e32 v192, s2, v142
	v_ashrrev_i32_e32 v193, 31, v192
	v_lshlrev_b64 v[192:193], 12, v[192:193]
	v_lshl_add_u64 v[192:193], s[42:43], 0, v[192:193]
	v_lshl_add_u64 v[192:193], v[192:193], 0, v[194:195]
	s_and_b64 vcc, exec, s[40:41]
	s_mov_b32 s36, s4
	s_mov_b32 s6, s48
	s_mov_b64 s[14:15], s[10:11]
	s_mov_b64 s[12:13], s[8:9]
	v_cvt_pk_bf16_f32 v196, v124, v125
	v_cvt_pk_bf16_f32 v197, v126, v127
	v_cvt_pk_bf16_f32 v198, v120, v121
	v_cvt_pk_bf16_f32 v199, v122, v123
	s_nop 1
	v_permlane16_swap_b32_e32 v196, v198
	v_permlane16_swap_b32_e32 v197, v199
	global_store_dwordx4 v[178:179], v[196:199], off
	v_cvt_pk_bf16_f32 v200, v112, v113
	v_cvt_pk_bf16_f32 v201, v114, v115
	v_cvt_pk_bf16_f32 v202, v108, v109
	v_cvt_pk_bf16_f32 v203, v110, v111
	s_nop 1
	v_permlane16_swap_b32_e32 v200, v202
	v_permlane16_swap_b32_e32 v201, v203
	global_store_dwordx4 v[178:179], v[200:203], off offset:256
	v_cvt_pk_bf16_f32 v150, v116, v117
	v_cvt_pk_bf16_f32 v151, v118, v119
	v_cvt_pk_bf16_f32 v152, v104, v105
	v_cvt_pk_bf16_f32 v153, v106, v107
	s_nop 1
	v_permlane16_swap_b32_e32 v150, v152
	v_permlane16_swap_b32_e32 v151, v153
	global_store_dwordx4 v[180:181], v[150:153], off
	v_cvt_pk_bf16_f32 v154, v96, v97
	v_cvt_pk_bf16_f32 v155, v98, v99
	v_cvt_pk_bf16_f32 v156, v92, v93
	v_cvt_pk_bf16_f32 v157, v94, v95
	s_nop 1
	v_permlane16_swap_b32_e32 v154, v156
	v_permlane16_swap_b32_e32 v155, v157
	global_store_dwordx4 v[180:181], v[154:157], off offset:256
	v_cvt_pk_bf16_f32 v196, v100, v101
	v_cvt_pk_bf16_f32 v197, v102, v103
	v_cvt_pk_bf16_f32 v198, v88, v89
	v_cvt_pk_bf16_f32 v199, v90, v91
	s_nop 1
	v_permlane16_swap_b32_e32 v196, v198
	v_permlane16_swap_b32_e32 v197, v199
	global_store_dwordx4 v[182:183], v[196:199], off
	v_cvt_pk_bf16_f32 v200, v80, v81
	v_cvt_pk_bf16_f32 v201, v82, v83
	v_cvt_pk_bf16_f32 v202, v76, v77
	v_cvt_pk_bf16_f32 v203, v78, v79
	s_nop 1
	v_permlane16_swap_b32_e32 v200, v202
	v_permlane16_swap_b32_e32 v201, v203
	global_store_dwordx4 v[182:183], v[200:203], off offset:256
	v_cvt_pk_bf16_f32 v150, v84, v85
	v_cvt_pk_bf16_f32 v151, v86, v87
	v_cvt_pk_bf16_f32 v152, v72, v73
	v_cvt_pk_bf16_f32 v153, v74, v75
	s_nop 1
	v_permlane16_swap_b32_e32 v150, v152
	v_permlane16_swap_b32_e32 v151, v153
	global_store_dwordx4 v[184:185], v[150:153], off
	v_cvt_pk_bf16_f32 v154, v68, v69
	v_cvt_pk_bf16_f32 v155, v70, v71
	v_cvt_pk_bf16_f32 v156, v64, v65
	v_cvt_pk_bf16_f32 v157, v66, v67
	s_nop 1
	v_permlane16_swap_b32_e32 v154, v156
	v_permlane16_swap_b32_e32 v155, v157
	global_store_dwordx4 v[184:185], v[154:157], off offset:256
	v_cvt_pk_bf16_f32 v196, v60, v61
	v_cvt_pk_bf16_f32 v197, v62, v63
	v_cvt_pk_bf16_f32 v198, v56, v57
	v_cvt_pk_bf16_f32 v199, v58, v59
	s_nop 1
	v_permlane16_swap_b32_e32 v196, v198
	v_permlane16_swap_b32_e32 v197, v199
	global_store_dwordx4 v[186:187], v[196:199], off
	v_cvt_pk_bf16_f32 v200, v48, v49
	v_cvt_pk_bf16_f32 v201, v50, v51
	v_cvt_pk_bf16_f32 v202, v44, v45
	v_cvt_pk_bf16_f32 v203, v46, v47
	s_nop 1
	v_permlane16_swap_b32_e32 v200, v202
	v_permlane16_swap_b32_e32 v201, v203
	global_store_dwordx4 v[186:187], v[200:203], off offset:256
	v_cvt_pk_bf16_f32 v150, v52, v53
	v_cvt_pk_bf16_f32 v151, v54, v55
	v_cvt_pk_bf16_f32 v152, v40, v41
	v_cvt_pk_bf16_f32 v153, v42, v43
	s_nop 1
	v_permlane16_swap_b32_e32 v150, v152
	v_permlane16_swap_b32_e32 v151, v153
	global_store_dwordx4 v[188:189], v[150:153], off
	v_cvt_pk_bf16_f32 v154, v32, v33
	v_cvt_pk_bf16_f32 v155, v34, v35
	v_cvt_pk_bf16_f32 v156, v28, v29
	v_cvt_pk_bf16_f32 v157, v30, v31
	s_nop 1
	v_permlane16_swap_b32_e32 v154, v156
	v_permlane16_swap_b32_e32 v155, v157
	global_store_dwordx4 v[188:189], v[154:157], off offset:256
	v_cvt_pk_bf16_f32 v196, v36, v37
	v_cvt_pk_bf16_f32 v197, v38, v39
	v_cvt_pk_bf16_f32 v198, v24, v25
	v_cvt_pk_bf16_f32 v199, v26, v27
	s_nop 1
	v_permlane16_swap_b32_e32 v196, v198
	v_permlane16_swap_b32_e32 v197, v199
	global_store_dwordx4 v[190:191], v[196:199], off
	v_cvt_pk_bf16_f32 v200, v16, v17
	v_cvt_pk_bf16_f32 v201, v18, v19
	v_cvt_pk_bf16_f32 v202, v12, v13
	v_cvt_pk_bf16_f32 v203, v14, v15
	s_nop 1
	v_permlane16_swap_b32_e32 v200, v202
	v_permlane16_swap_b32_e32 v201, v203
	global_store_dwordx4 v[190:191], v[200:203], off offset:256
	v_cvt_pk_bf16_f32 v150, v20, v21
	v_cvt_pk_bf16_f32 v151, v22, v23
	v_cvt_pk_bf16_f32 v152, v8, v9
	v_cvt_pk_bf16_f32 v153, v10, v11
	s_nop 1
	v_permlane16_swap_b32_e32 v150, v152
	v_permlane16_swap_b32_e32 v151, v153
	global_store_dwordx4 v[192:193], v[150:153], off
	v_cvt_pk_bf16_f32 v154, v4, v5
	v_cvt_pk_bf16_f32 v155, v6, v7
	v_cvt_pk_bf16_f32 v156, v0, v1
	v_cvt_pk_bf16_f32 v157, v2, v3
	s_nop 1
	v_permlane16_swap_b32_e32 v154, v156
	v_permlane16_swap_b32_e32 v155, v157
	global_store_dwordx4 v[192:193], v[154:157], off offset:256
	s_cbranch_vccz .LBB0_310
	s_waitcnt vmcnt(0)
	s_cmpk_gt_u32 s21, 0xff
	s_cbranch_scc1 .LBB0_321
	s_barrier
